# attn_combine: unrolled fast path with all 48 loads in flight (G=256, generic loop kept); barrier census loads batched
# speedup vs baseline: 1.0664x; 1.0018x over previous
; __device__ __forceinline__ unsigned xb_ld(unsigned* p)              { return __hip_atomic_load(p, __ATOMIC_RELAXED, __HIP_MEMORY_SCOPE_AGENT); }
; __device__ __forceinline__ void xcd_barrier_complete(unsigned* bar, unsigned x, unsigned& nloc, unsigned& nx) {
;     const unsigned G = gridDim.x * gridDim.y * gridDim.z;
;     unsigned sum, cnt, mine, sp = 0u;
;     for (;;) {
;         sum = 0u; cnt = 0u; mine = 0u;
; #pragma unroll
;         for (unsigned j = 0; j < 16; ++j) { const unsigned c = xb_ld(&bar[XB_XCNT(j)]); sum += c; cnt += (c > 0u) ? 1u : 0u; mine = (j == x) ? c : mine; }
;         if (sum == G) break;
;         __builtin_amdgcn_s_sleep(1);
;         if ((++sp & 255u) == 0u) { if (xb_ld(&bar[XB_TMO])) break; if (sp > XB_SPIN_CAP) { atomicAdd(&bar[XB_TMO], 1u); break; } }
;     }
.LBB0_286:
	v_readlane_b32 s4, v252, 6
	v_readlane_b32 s5, v252, 7
	v_readlane_b32 s6, v254, 10
	s_waitcnt lgkmcnt(0)
	s_nop 2
	global_load_dword v0, v65, s[4:5] sc1
	v_readlane_b32 s4, v252, 8
	v_readlane_b32 s5, v252, 9
	s_nop 4
	global_load_dword v1, v65, s[4:5] sc1
	v_readlane_b32 s4, v252, 10
	v_readlane_b32 s5, v252, 11
	s_nop 2
	s_nop 1
	global_load_dword v2, v65, s[4:5] sc1
	v_readlane_b32 s4, v252, 12
	v_readlane_b32 s5, v252, 13
	s_nop 2
	s_nop 1
	global_load_dword v3, v65, s[4:5] sc1
	v_readlane_b32 s4, v252, 14
	v_readlane_b32 s5, v252, 15
	s_nop 2
	s_nop 1
	global_load_dword v4, v65, s[4:5] sc1
	v_readlane_b32 s4, v252, 16
	v_readlane_b32 s5, v252, 17
	s_nop 2
	s_nop 1
	global_load_dword v5, v65, s[4:5] sc1
	v_readlane_b32 s4, v252, 18
	v_readlane_b32 s5, v252, 19
	s_nop 2
	s_nop 1
	global_load_dword v6, v65, s[4:5] sc1
	v_readlane_b32 s4, v252, 20
	v_readlane_b32 s5, v252, 21
	s_nop 2
	s_nop 1
	global_load_dword v7, v65, s[4:5] sc1
	v_readlane_b32 s4, v252, 22
	v_readlane_b32 s5, v252, 23
	s_nop 2
	s_nop 1
	global_load_dword v8, v65, s[4:5] sc1
	v_readlane_b32 s4, v252, 24
	v_readlane_b32 s5, v252, 25
	s_nop 2
	s_nop 1
	global_load_dword v9, v65, s[4:5] sc1
	v_readlane_b32 s4, v252, 26
	v_readlane_b32 s5, v252, 27
	s_nop 2
	s_nop 1
	global_load_dword v10, v65, s[4:5] sc1
	v_readlane_b32 s4, v252, 28
	v_readlane_b32 s5, v252, 29
	s_nop 2
	s_nop 1
	global_load_dword v11, v65, s[4:5] sc1
	v_readlane_b32 s4, v252, 30
	v_readlane_b32 s5, v252, 31
	s_nop 2
	s_nop 1
	global_load_dword v12, v65, s[4:5] sc1
	v_readlane_b32 s4, v252, 32
	v_readlane_b32 s5, v252, 33
	s_nop 2
	s_nop 1
	global_load_dword v13, v65, s[4:5] sc1
	v_readlane_b32 s4, v252, 34
	v_readlane_b32 s5, v252, 35
	s_nop 2
	s_nop 1
	global_load_dword v14, v65, s[4:5] sc1
	v_readlane_b32 s4, v252, 36
	v_readlane_b32 s5, v252, 37
	s_nop 2
	s_nop 1
	global_load_dword v15, v65, s[4:5] sc1
	s_mov_b64 s[4:5], -1
	s_waitcnt vmcnt(0)
	v_add_u32_e32 v16, v1, v0
	v_add_u32_e32 v16, v16, v2
	v_add_u32_e32 v16, v16, v3
	v_add_u32_e32 v16, v16, v4
	v_add_u32_e32 v16, v16, v5
	v_add_u32_e32 v16, v16, v6
	v_add_u32_e32 v16, v16, v7
	v_add_u32_e32 v16, v16, v8
	v_add_u32_e32 v16, v16, v9
	v_add_u32_e32 v16, v16, v10
	v_add_u32_e32 v16, v16, v11
	v_add_u32_e32 v16, v16, v12
	v_add_u32_e32 v16, v16, v13
	v_add_u32_e32 v16, v16, v14
	v_add_u32_e32 v16, v16, v15
	v_cmp_eq_u32_e32 vcc, s6, v16
	s_mov_b64 s[6:7], -1
	s_cbranch_vccnz .LBB0_285
	s_and_b32 s4, s10, 0xff
	s_cmp_eq_u32 s4, 0
	s_mov_b64 s[4:5], -1
	s_mov_b64 s[8:9], -1
	s_sleep 1
	s_cbranch_scc1 .LBB0_290
	s_and_b64 vcc, exec, s[8:9]
	s_cbranch_vccz .LBB0_285

; __device__ __forceinline__ unsigned cvt_pk_bf16(float lo, float hi) { f32x2_t v = {lo, hi}; bf2_t r = __builtin_convertvector(v, bf2_t); return __builtin_bit_cast(unsigned, r); }
; __device__ __forceinline__ float bflo(unsigned u) { return __uint_as_float(u << 16); }
; __device__ __forceinline__ float bfhi(unsigned u) { return __uint_as_float(u & 0xffff0000u); }
;     __device__ __forceinline__ bf16_t* bfp(size_t off) const { return (bf16_t*)(ws + off); }
;     __device__ __forceinline__ float* fp(size_t off) const { return (float*)(ws + off); }
; __device__ __forceinline__ void attn_combine(const Ctx& C) {
;     const bf16_t* pd = C.bfp(OFF_PROJD); const float* lse = C.fp(OFF_LSE); bf16_t* yd = C.bfp(OFF_YD);
;     for (int idx = C.bid * NTHR + C.tid; idx < M_TOK * 32; idx += C.G * NTHR) {
;         const int tok = idx >> 5, j = (idx >> 3) & 3, c8 = idx & 7;
;         const float l0 = lse[((size_t)0 * M_TOK + tok) * 4 + j], l1 = lse[((size_t)1 * M_TOK + tok) * 4 + j], l2 = lse[((size_t)2 * M_TOK + tok) * 4 + j];
;         const float mx = fmaxf(l0, fmaxf(l1, l2)); float w0 = __expf(l0 - mx), w1 = __expf(l1 - mx), w2 = __expf(l2 - mx); const float inv = 1.0f / (w0 + w1 + w2); w0 *= inv; w1 *= inv; w2 *= inv;
;         const bf16_t* row = pd + (size_t)tok * 2304 + j * 64 + c8 * 8;
;         const u32x4 o0 = *(const u32x4*)row, o1 = *(const u32x4*)(row + 256), o2 = *(const u32x4*)(row + 512);
;         u32x4 o;
;         o.x = cvt_pk_bf16(w0 * bflo(o0.x) + w1 * bflo(o1.x) + w2 * bflo(o2.x), w0 * bfhi(o0.x) + w1 * bfhi(o1.x) + w2 * bfhi(o2.x));
;         o.y = cvt_pk_bf16(w0 * bflo(o0.y) + w1 * bflo(o1.y) + w2 * bflo(o2.y), w0 * bfhi(o0.y) + w1 * bfhi(o1.y) + w2 * bfhi(o2.y));
;         o.z = cvt_pk_bf16(w0 * bflo(o0.z) + w1 * bflo(o1.z) + w2 * bflo(o2.z), w0 * bfhi(o0.z) + w1 * bfhi(o1.z) + w2 * bfhi(o2.z));
;         o.w = cvt_pk_bf16(w0 * bflo(o0.w) + w1 * bflo(o1.w) + w2 * bflo(o2.w), w0 * bfhi(o0.w) + w1 * bfhi(o1.w) + w2 * bfhi(o2.w));
;         *(u32x4*)(yd + (size_t)tok * 256 + j * 64 + c8 * 8) = o;
;     }
; }
.LBB0_751:
	s_cmpk_lg_i32 s26, 0x100
	s_cbranch_scc1 .Lmy_cmb_generic
	v_readlane_b32 s0, v253, 25
	s_add_u32 s4, s24, 0xe000000
	s_addc_u32 s5, s25, 0
	s_add_u32 s6, s24, 0x1a000000
	s_addc_u32 s7, s25, 0
	s_add_u32 s8, s24, 0x1b180000
	s_addc_u32 s9, s25, 0
	v_add_u32_e32 v0, s0, v224
	v_lshrrev_b32_e32 v1, 5, v0
	v_bfe_u32 v2, v0, 3, 2
	v_and_b32_e32 v3, 7, v0
	v_lshlrev_b32_e32 v4, 7, v2
	v_lshl_add_u32 v4, v3, 4, v4
	v_lshlrev_b32_e32 v5, 2, v2
	v_lshl_add_u32 v10, v1, 4, v5
	v_add_u32_e32 v11, 0x80000, v10
	v_add_u32_e32 v12, 0x100000, v10
	s_movk_i32 s0, 0x1200
	v_mad_u32_u24 v13, v1, s0, v4
	v_lshl_add_u32 v14, v1, 9, v4
	global_load_dword v164, v10, s[6:7]
	global_load_dword v165, v11, s[6:7]
	global_load_dword v166, v12, s[6:7]
	s_add_u32 s6, s6, 0x10000
	s_addc_u32 s7, s7, 0
	global_load_dword v167, v10, s[6:7]
	global_load_dword v168, v11, s[6:7]
	global_load_dword v169, v12, s[6:7]
	s_add_u32 s6, s6, 0x10000
	s_addc_u32 s7, s7, 0
	global_load_dword v170, v10, s[6:7]
	global_load_dword v171, v11, s[6:7]
	global_load_dword v172, v12, s[6:7]
	s_add_u32 s6, s6, 0x10000
	s_addc_u32 s7, s7, 0
	global_load_dword v173, v10, s[6:7]
	global_load_dword v174, v11, s[6:7]
	global_load_dword v175, v12, s[6:7]
	s_add_u32 s6, s6, 0x10000
	s_addc_u32 s7, s7, 0
	global_load_dword v176, v10, s[6:7]
	global_load_dword v177, v11, s[6:7]
	global_load_dword v178, v12, s[6:7]
	s_add_u32 s6, s6, 0x10000
	s_addc_u32 s7, s7, 0
	global_load_dword v179, v10, s[6:7]
	global_load_dword v180, v11, s[6:7]
	global_load_dword v181, v12, s[6:7]
	s_add_u32 s6, s6, 0x10000
	s_addc_u32 s7, s7, 0
	global_load_dword v188, v10, s[6:7]
	global_load_dword v189, v11, s[6:7]
	global_load_dword v190, v12, s[6:7]
	s_add_u32 s6, s6, 0x10000
	s_addc_u32 s7, s7, 0
	global_load_dword v191, v10, s[6:7]
	global_load_dword v192, v11, s[6:7]
	global_load_dword v193, v12, s[6:7]
	global_load_dwordx4 v[68:71], v13, s[4:5]
	global_load_dwordx4 v[72:75], v13, s[4:5] offset:512
	global_load_dwordx4 v[76:79], v13, s[4:5] offset:1024
	s_add_u32 s4, s4, 0x1200000
	s_addc_u32 s5, s5, 0
	global_load_dwordx4 v[80:83], v13, s[4:5]
	global_load_dwordx4 v[84:87], v13, s[4:5] offset:512
	global_load_dwordx4 v[88:91], v13, s[4:5] offset:1024
	s_add_u32 s4, s4, 0x1200000
	s_addc_u32 s5, s5, 0
	global_load_dwordx4 v[92:95], v13, s[4:5]
	global_load_dwordx4 v[96:99], v13, s[4:5] offset:512
	global_load_dwordx4 v[100:103], v13, s[4:5] offset:1024
	s_add_u32 s4, s4, 0x1200000
	s_addc_u32 s5, s5, 0
	global_load_dwordx4 v[104:107], v13, s[4:5]
	global_load_dwordx4 v[108:111], v13, s[4:5] offset:512
	global_load_dwordx4 v[112:115], v13, s[4:5] offset:1024
	s_add_u32 s4, s4, 0x1200000
	s_addc_u32 s5, s5, 0
	global_load_dwordx4 v[116:119], v13, s[4:5]
	global_load_dwordx4 v[120:123], v13, s[4:5] offset:512
	global_load_dwordx4 v[124:127], v13, s[4:5] offset:1024
	s_add_u32 s4, s4, 0x1200000
	s_addc_u32 s5, s5, 0
	global_load_dwordx4 v[128:131], v13, s[4:5]
	global_load_dwordx4 v[132:135], v13, s[4:5] offset:512
	global_load_dwordx4 v[136:139], v13, s[4:5] offset:1024
	s_add_u32 s4, s4, 0x1200000
	s_addc_u32 s5, s5, 0
	global_load_dwordx4 v[140:143], v13, s[4:5]
	global_load_dwordx4 v[144:147], v13, s[4:5] offset:512
	global_load_dwordx4 v[148:151], v13, s[4:5] offset:1024
	s_add_u32 s4, s4, 0x1200000
	s_addc_u32 s5, s5, 0
	global_load_dwordx4 v[152:155], v13, s[4:5]
	global_load_dwordx4 v[156:159], v13, s[4:5] offset:512
	global_load_dwordx4 v[160:163], v13, s[4:5] offset:1024
	s_waitcnt vmcnt(45)
	v_max3_f32 v20, v164, v165, v166
	v_sub_f32_e32 v21, v164, v20
	v_sub_f32_e32 v22, v165, v20
	v_sub_f32_e32 v23, v166, v20
	v_mul_f32_e32 v21, 0x3fb8aa3b, v21
	v_mul_f32_e32 v22, 0x3fb8aa3b, v22
	v_mul_f32_e32 v23, 0x3fb8aa3b, v23
	v_exp_f32_e32 v21, v21
	v_exp_f32_e32 v22, v22
	v_exp_f32_e32 v23, v23
	s_nop 0
	v_add_f32_e32 v24, v21, v22
	v_add_f32_e32 v24, v23, v24
	v_rcp_f32_e32 v24, v24
	s_nop 0
	v_mul_f32_e32 v21, v21, v24
	v_mul_f32_e32 v22, v22, v24
	v_mul_f32_e32 v23, v23, v24
	s_waitcnt vmcnt(21)
	v_lshlrev_b32_e32 v25, 16, v68
	v_and_b32_e32 v26, 0xffff0000, v68
	v_lshlrev_b32_e32 v27, 16, v72
	v_and_b32_e32 v28, 0xffff0000, v72
	v_lshlrev_b32_e32 v29, 16, v76
	v_and_b32_e32 v30, 0xffff0000, v76
	v_mul_f32_e32 v31, v21, v25
	v_mul_f32_e32 v32, v22, v28
	v_fmac_f32_e32 v31, v22, v27
	v_fmac_f32_e32 v32, v21, v26
	v_fmac_f32_e32 v31, v23, v29
	v_fmac_f32_e32 v32, v23, v30
	v_cvt_pk_bf16_f32 v68, v31, v32
	v_lshlrev_b32_e32 v25, 16, v69
	v_and_b32_e32 v26, 0xffff0000, v69
	v_lshlrev_b32_e32 v27, 16, v73
	v_and_b32_e32 v28, 0xffff0000, v73
	v_lshlrev_b32_e32 v29, 16, v77
	v_and_b32_e32 v30, 0xffff0000, v77
	v_mul_f32_e32 v31, v21, v25
	v_mul_f32_e32 v32, v22, v28
	v_fmac_f32_e32 v31, v22, v27
	v_fmac_f32_e32 v32, v21, v26
	v_fmac_f32_e32 v31, v23, v29
	v_fmac_f32_e32 v32, v23, v30
	v_cvt_pk_bf16_f32 v69, v31, v32
	v_lshlrev_b32_e32 v25, 16, v70
	v_and_b32_e32 v26, 0xffff0000, v70
	v_lshlrev_b32_e32 v27, 16, v74
	v_and_b32_e32 v28, 0xffff0000, v74
	v_lshlrev_b32_e32 v29, 16, v78
	v_and_b32_e32 v30, 0xffff0000, v78
	v_mul_f32_e32 v31, v21, v25
	v_mul_f32_e32 v32, v22, v28
	v_fmac_f32_e32 v31, v22, v27
	v_fmac_f32_e32 v32, v21, v26
	v_fmac_f32_e32 v31, v23, v29
	v_fmac_f32_e32 v32, v23, v30
	v_cvt_pk_bf16_f32 v70, v31, v32
	v_lshlrev_b32_e32 v25, 16, v71
	v_and_b32_e32 v26, 0xffff0000, v71
	v_lshlrev_b32_e32 v27, 16, v75
	v_and_b32_e32 v28, 0xffff0000, v75
	v_lshlrev_b32_e32 v29, 16, v79
	v_and_b32_e32 v30, 0xffff0000, v79
	v_mul_f32_e32 v31, v21, v25
	v_mul_f32_e32 v32, v22, v28
	v_fmac_f32_e32 v31, v22, v27
	v_fmac_f32_e32 v32, v21, v26
	v_fmac_f32_e32 v31, v23, v29
	v_fmac_f32_e32 v32, v23, v30
	v_cvt_pk_bf16_f32 v71, v31, v32
	global_store_dwordx4 v14, v[68:71], s[8:9]
	s_add_u32 s8, s8, 0x200000
	s_addc_u32 s9, s9, 0
	v_max3_f32 v20, v167, v168, v169
	v_sub_f32_e32 v21, v167, v20
	v_sub_f32_e32 v22, v168, v20
	v_sub_f32_e32 v23, v169, v20
	v_mul_f32_e32 v21, 0x3fb8aa3b, v21
	v_mul_f32_e32 v22, 0x3fb8aa3b, v22
	v_mul_f32_e32 v23, 0x3fb8aa3b, v23
	v_exp_f32_e32 v21, v21
	v_exp_f32_e32 v22, v22
	v_exp_f32_e32 v23, v23
	s_nop 0
	v_add_f32_e32 v24, v21, v22
	v_add_f32_e32 v24, v23, v24
	v_rcp_f32_e32 v24, v24
	s_nop 0
	v_mul_f32_e32 v21, v21, v24
	v_mul_f32_e32 v22, v22, v24
	v_mul_f32_e32 v23, v23, v24
	s_waitcnt vmcnt(19)
; __device__ __forceinline__ unsigned cvt_pk_bf16(float lo, float hi) { f32x2_t v = {lo, hi}; bf2_t r = __builtin_convertvector(v, bf2_t); return __builtin_bit_cast(unsigned, r); }
; __device__ __forceinline__ float bflo(unsigned u) { return __uint_as_float(u << 16); }
; __device__ __forceinline__ float bfhi(unsigned u) { return __uint_as_float(u & 0xffff0000u); }
;     __device__ __forceinline__ bf16_t* bfp(size_t off) const { return (bf16_t*)(ws + off); }
;     __device__ __forceinline__ float* fp(size_t off) const { return (float*)(ws + off); }
; __device__ __forceinline__ void attn_combine(const Ctx& C) {
;     const bf16_t* pd = C.bfp(OFF_PROJD); const float* lse = C.fp(OFF_LSE); bf16_t* yd = C.bfp(OFF_YD);
;     for (int idx = C.bid * NTHR + C.tid; idx < M_TOK * 32; idx += C.G * NTHR) {
;         const int tok = idx >> 5, j = (idx >> 3) & 3, c8 = idx & 7;
;         const float l0 = lse[((size_t)0 * M_TOK + tok) * 4 + j], l1 = lse[((size_t)1 * M_TOK + tok) * 4 + j], l2 = lse[((size_t)2 * M_TOK + tok) * 4 + j];
;         const float mx = fmaxf(l0, fmaxf(l1, l2)); float w0 = __expf(l0 - mx), w1 = __expf(l1 - mx), w2 = __expf(l2 - mx); const float inv = 1.0f / (w0 + w1 + w2); w0 *= inv; w1 *= inv; w2 *= inv;
;         const bf16_t* row = pd + (size_t)tok * 2304 + j * 64 + c8 * 8;
;         const u32x4 o0 = *(const u32x4*)row, o1 = *(const u32x4*)(row + 256), o2 = *(const u32x4*)(row + 512);
;         u32x4 o;
;         o.x = cvt_pk_bf16(w0 * bflo(o0.x) + w1 * bflo(o1.x) + w2 * bflo(o2.x), w0 * bfhi(o0.x) + w1 * bfhi(o1.x) + w2 * bfhi(o2.x));
;         o.y = cvt_pk_bf16(w0 * bflo(o0.y) + w1 * bflo(o1.y) + w2 * bflo(o2.y), w0 * bfhi(o0.y) + w1 * bfhi(o1.y) + w2 * bfhi(o2.y));
;         o.z = cvt_pk_bf16(w0 * bflo(o0.z) + w1 * bflo(o1.z) + w2 * bflo(o2.z), w0 * bfhi(o0.z) + w1 * bfhi(o1.z) + w2 * bfhi(o2.z));
;         o.w = cvt_pk_bf16(w0 * bflo(o0.w) + w1 * bflo(o1.w) + w2 * bflo(o2.w), w0 * bfhi(o0.w) + w1 * bfhi(o1.w) + w2 * bfhi(o2.w));
;         *(u32x4*)(yd + (size_t)tok * 256 + j * 64 + c8 * 8) = o;
;     }
; }
	v_lshlrev_b32_e32 v25, 16, v80
	v_and_b32_e32 v26, 0xffff0000, v80
	v_lshlrev_b32_e32 v27, 16, v84
	v_and_b32_e32 v28, 0xffff0000, v84
	v_lshlrev_b32_e32 v29, 16, v88
	v_and_b32_e32 v30, 0xffff0000, v88
	v_mul_f32_e32 v31, v21, v25
	v_mul_f32_e32 v32, v22, v28
	v_fmac_f32_e32 v31, v22, v27
	v_fmac_f32_e32 v32, v21, v26
	v_fmac_f32_e32 v31, v23, v29
	v_fmac_f32_e32 v32, v23, v30
	v_cvt_pk_bf16_f32 v80, v31, v32
	v_lshlrev_b32_e32 v25, 16, v81
	v_and_b32_e32 v26, 0xffff0000, v81
	v_lshlrev_b32_e32 v27, 16, v85
	v_and_b32_e32 v28, 0xffff0000, v85
	v_lshlrev_b32_e32 v29, 16, v89
	v_and_b32_e32 v30, 0xffff0000, v89
	v_mul_f32_e32 v31, v21, v25
	v_mul_f32_e32 v32, v22, v28
	v_fmac_f32_e32 v31, v22, v27
	v_fmac_f32_e32 v32, v21, v26
	v_fmac_f32_e32 v31, v23, v29
	v_fmac_f32_e32 v32, v23, v30
	v_cvt_pk_bf16_f32 v81, v31, v32
	v_lshlrev_b32_e32 v25, 16, v82
	v_and_b32_e32 v26, 0xffff0000, v82
	v_lshlrev_b32_e32 v27, 16, v86
	v_and_b32_e32 v28, 0xffff0000, v86
	v_lshlrev_b32_e32 v29, 16, v90
	v_and_b32_e32 v30, 0xffff0000, v90
	v_mul_f32_e32 v31, v21, v25
	v_mul_f32_e32 v32, v22, v28
	v_fmac_f32_e32 v31, v22, v27
	v_fmac_f32_e32 v32, v21, v26
	v_fmac_f32_e32 v31, v23, v29
	v_fmac_f32_e32 v32, v23, v30
	v_cvt_pk_bf16_f32 v82, v31, v32
	v_lshlrev_b32_e32 v25, 16, v83
	v_and_b32_e32 v26, 0xffff0000, v83
	v_lshlrev_b32_e32 v27, 16, v87
	v_and_b32_e32 v28, 0xffff0000, v87
	v_lshlrev_b32_e32 v29, 16, v91
	v_and_b32_e32 v30, 0xffff0000, v91
	v_mul_f32_e32 v31, v21, v25
	v_mul_f32_e32 v32, v22, v28
	v_fmac_f32_e32 v31, v22, v27
	v_fmac_f32_e32 v32, v21, v26
	v_fmac_f32_e32 v31, v23, v29
	v_fmac_f32_e32 v32, v23, v30
	v_cvt_pk_bf16_f32 v83, v31, v32
	global_store_dwordx4 v14, v[80:83], s[8:9]
	s_add_u32 s8, s8, 0x200000
	s_addc_u32 s9, s9, 0
	v_max3_f32 v20, v170, v171, v172
	v_sub_f32_e32 v21, v170, v20
	v_sub_f32_e32 v22, v171, v20
	v_sub_f32_e32 v23, v172, v20
	v_mul_f32_e32 v21, 0x3fb8aa3b, v21
	v_mul_f32_e32 v22, 0x3fb8aa3b, v22
	v_mul_f32_e32 v23, 0x3fb8aa3b, v23
	v_exp_f32_e32 v21, v21
	v_exp_f32_e32 v22, v22
	v_exp_f32_e32 v23, v23
	s_nop 0
	v_add_f32_e32 v24, v21, v22
	v_add_f32_e32 v24, v23, v24
	v_rcp_f32_e32 v24, v24
	s_nop 0
	v_mul_f32_e32 v21, v21, v24
	v_mul_f32_e32 v22, v22, v24
	v_mul_f32_e32 v23, v23, v24
	s_waitcnt vmcnt(17)
	v_lshlrev_b32_e32 v25, 16, v92
	v_and_b32_e32 v26, 0xffff0000, v92
	v_lshlrev_b32_e32 v27, 16, v96
	v_and_b32_e32 v28, 0xffff0000, v96
	v_lshlrev_b32_e32 v29, 16, v100
	v_and_b32_e32 v30, 0xffff0000, v100
	v_mul_f32_e32 v31, v21, v25
	v_mul_f32_e32 v32, v22, v28
	v_fmac_f32_e32 v31, v22, v27
	v_fmac_f32_e32 v32, v21, v26
	v_fmac_f32_e32 v31, v23, v29
	v_fmac_f32_e32 v32, v23, v30
	v_cvt_pk_bf16_f32 v92, v31, v32
	v_lshlrev_b32_e32 v25, 16, v93
	v_and_b32_e32 v26, 0xffff0000, v93
	v_lshlrev_b32_e32 v27, 16, v97
	v_and_b32_e32 v28, 0xffff0000, v97
	v_lshlrev_b32_e32 v29, 16, v101
	v_and_b32_e32 v30, 0xffff0000, v101
	v_mul_f32_e32 v31, v21, v25
	v_mul_f32_e32 v32, v22, v28
	v_fmac_f32_e32 v31, v22, v27
	v_fmac_f32_e32 v32, v21, v26
	v_fmac_f32_e32 v31, v23, v29
	v_fmac_f32_e32 v32, v23, v30
	v_cvt_pk_bf16_f32 v93, v31, v32
	v_lshlrev_b32_e32 v25, 16, v94
	v_and_b32_e32 v26, 0xffff0000, v94
	v_lshlrev_b32_e32 v27, 16, v98
	v_and_b32_e32 v28, 0xffff0000, v98
	v_lshlrev_b32_e32 v29, 16, v102
	v_and_b32_e32 v30, 0xffff0000, v102
	v_mul_f32_e32 v31, v21, v25
	v_mul_f32_e32 v32, v22, v28
	v_fmac_f32_e32 v31, v22, v27
	v_fmac_f32_e32 v32, v21, v26
	v_fmac_f32_e32 v31, v23, v29
	v_fmac_f32_e32 v32, v23, v30
	v_cvt_pk_bf16_f32 v94, v31, v32
	v_lshlrev_b32_e32 v25, 16, v95
	v_and_b32_e32 v26, 0xffff0000, v95
	v_lshlrev_b32_e32 v27, 16, v99
	v_and_b32_e32 v28, 0xffff0000, v99
	v_lshlrev_b32_e32 v29, 16, v103
	v_and_b32_e32 v30, 0xffff0000, v103
	v_mul_f32_e32 v31, v21, v25
	v_mul_f32_e32 v32, v22, v28
	v_fmac_f32_e32 v31, v22, v27
	v_fmac_f32_e32 v32, v21, v26
	v_fmac_f32_e32 v31, v23, v29
	v_fmac_f32_e32 v32, v23, v30
	v_cvt_pk_bf16_f32 v95, v31, v32
	global_store_dwordx4 v14, v[92:95], s[8:9]
	s_add_u32 s8, s8, 0x200000
	s_addc_u32 s9, s9, 0
	v_max3_f32 v20, v173, v174, v175
	v_sub_f32_e32 v21, v173, v20
	v_sub_f32_e32 v22, v174, v20
	v_sub_f32_e32 v23, v175, v20
	v_mul_f32_e32 v21, 0x3fb8aa3b, v21
	v_mul_f32_e32 v22, 0x3fb8aa3b, v22
	v_mul_f32_e32 v23, 0x3fb8aa3b, v23
	v_exp_f32_e32 v21, v21
	v_exp_f32_e32 v22, v22
	v_exp_f32_e32 v23, v23
	s_nop 0
	v_add_f32_e32 v24, v21, v22
	v_add_f32_e32 v24, v23, v24
	v_rcp_f32_e32 v24, v24
	s_nop 0
	v_mul_f32_e32 v21, v21, v24
	v_mul_f32_e32 v22, v22, v24
	v_mul_f32_e32 v23, v23, v24
	s_waitcnt vmcnt(15)
; __device__ __forceinline__ unsigned cvt_pk_bf16(float lo, float hi) { f32x2_t v = {lo, hi}; bf2_t r = __builtin_convertvector(v, bf2_t); return __builtin_bit_cast(unsigned, r); }
; __device__ __forceinline__ float bflo(unsigned u) { return __uint_as_float(u << 16); }
; __device__ __forceinline__ float bfhi(unsigned u) { return __uint_as_float(u & 0xffff0000u); }
;     __device__ __forceinline__ bf16_t* bfp(size_t off) const { return (bf16_t*)(ws + off); }
;     __device__ __forceinline__ float* fp(size_t off) const { return (float*)(ws + off); }
; __device__ __forceinline__ void attn_combine(const Ctx& C) {
;     const bf16_t* pd = C.bfp(OFF_PROJD); const float* lse = C.fp(OFF_LSE); bf16_t* yd = C.bfp(OFF_YD);
;     for (int idx = C.bid * NTHR + C.tid; idx < M_TOK * 32; idx += C.G * NTHR) {
;         const int tok = idx >> 5, j = (idx >> 3) & 3, c8 = idx & 7;
;         const float l0 = lse[((size_t)0 * M_TOK + tok) * 4 + j], l1 = lse[((size_t)1 * M_TOK + tok) * 4 + j], l2 = lse[((size_t)2 * M_TOK + tok) * 4 + j];
;         const float mx = fmaxf(l0, fmaxf(l1, l2)); float w0 = __expf(l0 - mx), w1 = __expf(l1 - mx), w2 = __expf(l2 - mx); const float inv = 1.0f / (w0 + w1 + w2); w0 *= inv; w1 *= inv; w2 *= inv;
;         const bf16_t* row = pd + (size_t)tok * 2304 + j * 64 + c8 * 8;
;         const u32x4 o0 = *(const u32x4*)row, o1 = *(const u32x4*)(row + 256), o2 = *(const u32x4*)(row + 512);
;         u32x4 o;
;         o.x = cvt_pk_bf16(w0 * bflo(o0.x) + w1 * bflo(o1.x) + w2 * bflo(o2.x), w0 * bfhi(o0.x) + w1 * bfhi(o1.x) + w2 * bfhi(o2.x));
;         o.y = cvt_pk_bf16(w0 * bflo(o0.y) + w1 * bflo(o1.y) + w2 * bflo(o2.y), w0 * bfhi(o0.y) + w1 * bfhi(o1.y) + w2 * bfhi(o2.y));
;         o.z = cvt_pk_bf16(w0 * bflo(o0.z) + w1 * bflo(o1.z) + w2 * bflo(o2.z), w0 * bfhi(o0.z) + w1 * bfhi(o1.z) + w2 * bfhi(o2.z));
;         o.w = cvt_pk_bf16(w0 * bflo(o0.w) + w1 * bflo(o1.w) + w2 * bflo(o2.w), w0 * bfhi(o0.w) + w1 * bfhi(o1.w) + w2 * bfhi(o2.w));
;         *(u32x4*)(yd + (size_t)tok * 256 + j * 64 + c8 * 8) = o;
;     }
; }
	v_lshlrev_b32_e32 v25, 16, v104
	v_and_b32_e32 v26, 0xffff0000, v104
	v_lshlrev_b32_e32 v27, 16, v108
	v_and_b32_e32 v28, 0xffff0000, v108
	v_lshlrev_b32_e32 v29, 16, v112
	v_and_b32_e32 v30, 0xffff0000, v112
	v_mul_f32_e32 v31, v21, v25
	v_mul_f32_e32 v32, v22, v28
	v_fmac_f32_e32 v31, v22, v27
	v_fmac_f32_e32 v32, v21, v26
	v_fmac_f32_e32 v31, v23, v29
	v_fmac_f32_e32 v32, v23, v30
	v_cvt_pk_bf16_f32 v104, v31, v32
	v_lshlrev_b32_e32 v25, 16, v105
	v_and_b32_e32 v26, 0xffff0000, v105
	v_lshlrev_b32_e32 v27, 16, v109
	v_and_b32_e32 v28, 0xffff0000, v109
	v_lshlrev_b32_e32 v29, 16, v113
	v_and_b32_e32 v30, 0xffff0000, v113
	v_mul_f32_e32 v31, v21, v25
	v_mul_f32_e32 v32, v22, v28
	v_fmac_f32_e32 v31, v22, v27
	v_fmac_f32_e32 v32, v21, v26
	v_fmac_f32_e32 v31, v23, v29
	v_fmac_f32_e32 v32, v23, v30
	v_cvt_pk_bf16_f32 v105, v31, v32
	v_lshlrev_b32_e32 v25, 16, v106
	v_and_b32_e32 v26, 0xffff0000, v106
	v_lshlrev_b32_e32 v27, 16, v110
	v_and_b32_e32 v28, 0xffff0000, v110
	v_lshlrev_b32_e32 v29, 16, v114
	v_and_b32_e32 v30, 0xffff0000, v114
	v_mul_f32_e32 v31, v21, v25
	v_mul_f32_e32 v32, v22, v28
	v_fmac_f32_e32 v31, v22, v27
	v_fmac_f32_e32 v32, v21, v26
	v_fmac_f32_e32 v31, v23, v29
	v_fmac_f32_e32 v32, v23, v30
	v_cvt_pk_bf16_f32 v106, v31, v32
	v_lshlrev_b32_e32 v25, 16, v107
	v_and_b32_e32 v26, 0xffff0000, v107
	v_lshlrev_b32_e32 v27, 16, v111
	v_and_b32_e32 v28, 0xffff0000, v111
	v_lshlrev_b32_e32 v29, 16, v115
	v_and_b32_e32 v30, 0xffff0000, v115
	v_mul_f32_e32 v31, v21, v25
	v_mul_f32_e32 v32, v22, v28
	v_fmac_f32_e32 v31, v22, v27
	v_fmac_f32_e32 v32, v21, v26
	v_fmac_f32_e32 v31, v23, v29
	v_fmac_f32_e32 v32, v23, v30
	v_cvt_pk_bf16_f32 v107, v31, v32
	global_store_dwordx4 v14, v[104:107], s[8:9]
	s_add_u32 s8, s8, 0x200000
	s_addc_u32 s9, s9, 0
	v_max3_f32 v20, v176, v177, v178
	v_sub_f32_e32 v21, v176, v20
	v_sub_f32_e32 v22, v177, v20
	v_sub_f32_e32 v23, v178, v20
	v_mul_f32_e32 v21, 0x3fb8aa3b, v21
	v_mul_f32_e32 v22, 0x3fb8aa3b, v22
	v_mul_f32_e32 v23, 0x3fb8aa3b, v23
	v_exp_f32_e32 v21, v21
	v_exp_f32_e32 v22, v22
	v_exp_f32_e32 v23, v23
	s_nop 0
	v_add_f32_e32 v24, v21, v22
	v_add_f32_e32 v24, v23, v24
	v_rcp_f32_e32 v24, v24
	s_nop 0
	v_mul_f32_e32 v21, v21, v24
	v_mul_f32_e32 v22, v22, v24
	v_mul_f32_e32 v23, v23, v24
	s_waitcnt vmcnt(13)
	v_lshlrev_b32_e32 v25, 16, v116
	v_and_b32_e32 v26, 0xffff0000, v116
	v_lshlrev_b32_e32 v27, 16, v120
	v_and_b32_e32 v28, 0xffff0000, v120
	v_lshlrev_b32_e32 v29, 16, v124
	v_and_b32_e32 v30, 0xffff0000, v124
	v_mul_f32_e32 v31, v21, v25
	v_mul_f32_e32 v32, v22, v28
	v_fmac_f32_e32 v31, v22, v27
	v_fmac_f32_e32 v32, v21, v26
	v_fmac_f32_e32 v31, v23, v29
	v_fmac_f32_e32 v32, v23, v30
	v_cvt_pk_bf16_f32 v116, v31, v32
	v_lshlrev_b32_e32 v25, 16, v117
	v_and_b32_e32 v26, 0xffff0000, v117
	v_lshlrev_b32_e32 v27, 16, v121
	v_and_b32_e32 v28, 0xffff0000, v121
	v_lshlrev_b32_e32 v29, 16, v125
	v_and_b32_e32 v30, 0xffff0000, v125
	v_mul_f32_e32 v31, v21, v25
	v_mul_f32_e32 v32, v22, v28
	v_fmac_f32_e32 v31, v22, v27
	v_fmac_f32_e32 v32, v21, v26
	v_fmac_f32_e32 v31, v23, v29
	v_fmac_f32_e32 v32, v23, v30
	v_cvt_pk_bf16_f32 v117, v31, v32
	v_lshlrev_b32_e32 v25, 16, v118
	v_and_b32_e32 v26, 0xffff0000, v118
	v_lshlrev_b32_e32 v27, 16, v122
	v_and_b32_e32 v28, 0xffff0000, v122
	v_lshlrev_b32_e32 v29, 16, v126
	v_and_b32_e32 v30, 0xffff0000, v126
	v_mul_f32_e32 v31, v21, v25
	v_mul_f32_e32 v32, v22, v28
	v_fmac_f32_e32 v31, v22, v27
	v_fmac_f32_e32 v32, v21, v26
	v_fmac_f32_e32 v31, v23, v29
	v_fmac_f32_e32 v32, v23, v30
	v_cvt_pk_bf16_f32 v118, v31, v32
	v_lshlrev_b32_e32 v25, 16, v119
	v_and_b32_e32 v26, 0xffff0000, v119
	v_lshlrev_b32_e32 v27, 16, v123
	v_and_b32_e32 v28, 0xffff0000, v123
	v_lshlrev_b32_e32 v29, 16, v127
	v_and_b32_e32 v30, 0xffff0000, v127
	v_mul_f32_e32 v31, v21, v25
	v_mul_f32_e32 v32, v22, v28
	v_fmac_f32_e32 v31, v22, v27
	v_fmac_f32_e32 v32, v21, v26
	v_fmac_f32_e32 v31, v23, v29
	v_fmac_f32_e32 v32, v23, v30
	v_cvt_pk_bf16_f32 v119, v31, v32
	global_store_dwordx4 v14, v[116:119], s[8:9]
	s_add_u32 s8, s8, 0x200000
	s_addc_u32 s9, s9, 0
	v_max3_f32 v20, v179, v180, v181
	v_sub_f32_e32 v21, v179, v20
	v_sub_f32_e32 v22, v180, v20
	v_sub_f32_e32 v23, v181, v20
	v_mul_f32_e32 v21, 0x3fb8aa3b, v21
	v_mul_f32_e32 v22, 0x3fb8aa3b, v22
	v_mul_f32_e32 v23, 0x3fb8aa3b, v23
	v_exp_f32_e32 v21, v21
	v_exp_f32_e32 v22, v22
	v_exp_f32_e32 v23, v23
	s_nop 0
	v_add_f32_e32 v24, v21, v22
	v_add_f32_e32 v24, v23, v24
	v_rcp_f32_e32 v24, v24
	s_nop 0
	v_mul_f32_e32 v21, v21, v24
	v_mul_f32_e32 v22, v22, v24
	v_mul_f32_e32 v23, v23, v24
	s_waitcnt vmcnt(11)
; __device__ __forceinline__ unsigned cvt_pk_bf16(float lo, float hi) { f32x2_t v = {lo, hi}; bf2_t r = __builtin_convertvector(v, bf2_t); return __builtin_bit_cast(unsigned, r); }
; __device__ __forceinline__ float bflo(unsigned u) { return __uint_as_float(u << 16); }
; __device__ __forceinline__ float bfhi(unsigned u) { return __uint_as_float(u & 0xffff0000u); }
;     __device__ __forceinline__ bf16_t* bfp(size_t off) const { return (bf16_t*)(ws + off); }
;     __device__ __forceinline__ float* fp(size_t off) const { return (float*)(ws + off); }
; __device__ __forceinline__ void attn_combine(const Ctx& C) {
;     const bf16_t* pd = C.bfp(OFF_PROJD); const float* lse = C.fp(OFF_LSE); bf16_t* yd = C.bfp(OFF_YD);
;     for (int idx = C.bid * NTHR + C.tid; idx < M_TOK * 32; idx += C.G * NTHR) {
;         const int tok = idx >> 5, j = (idx >> 3) & 3, c8 = idx & 7;
;         const float l0 = lse[((size_t)0 * M_TOK + tok) * 4 + j], l1 = lse[((size_t)1 * M_TOK + tok) * 4 + j], l2 = lse[((size_t)2 * M_TOK + tok) * 4 + j];
;         const float mx = fmaxf(l0, fmaxf(l1, l2)); float w0 = __expf(l0 - mx), w1 = __expf(l1 - mx), w2 = __expf(l2 - mx); const float inv = 1.0f / (w0 + w1 + w2); w0 *= inv; w1 *= inv; w2 *= inv;
;         const bf16_t* row = pd + (size_t)tok * 2304 + j * 64 + c8 * 8;
;         const u32x4 o0 = *(const u32x4*)row, o1 = *(const u32x4*)(row + 256), o2 = *(const u32x4*)(row + 512);
;         u32x4 o;
;         o.x = cvt_pk_bf16(w0 * bflo(o0.x) + w1 * bflo(o1.x) + w2 * bflo(o2.x), w0 * bfhi(o0.x) + w1 * bfhi(o1.x) + w2 * bfhi(o2.x));
;         o.y = cvt_pk_bf16(w0 * bflo(o0.y) + w1 * bflo(o1.y) + w2 * bflo(o2.y), w0 * bfhi(o0.y) + w1 * bfhi(o1.y) + w2 * bfhi(o2.y));
;         o.z = cvt_pk_bf16(w0 * bflo(o0.z) + w1 * bflo(o1.z) + w2 * bflo(o2.z), w0 * bfhi(o0.z) + w1 * bfhi(o1.z) + w2 * bfhi(o2.z));
;         o.w = cvt_pk_bf16(w0 * bflo(o0.w) + w1 * bflo(o1.w) + w2 * bflo(o2.w), w0 * bfhi(o0.w) + w1 * bfhi(o1.w) + w2 * bfhi(o2.w));
;         *(u32x4*)(yd + (size_t)tok * 256 + j * 64 + c8 * 8) = o;
;     }
; }
	v_lshlrev_b32_e32 v25, 16, v128
	v_and_b32_e32 v26, 0xffff0000, v128
	v_lshlrev_b32_e32 v27, 16, v132
	v_and_b32_e32 v28, 0xffff0000, v132
	v_lshlrev_b32_e32 v29, 16, v136
	v_and_b32_e32 v30, 0xffff0000, v136
	v_mul_f32_e32 v31, v21, v25
	v_mul_f32_e32 v32, v22, v28
	v_fmac_f32_e32 v31, v22, v27
	v_fmac_f32_e32 v32, v21, v26
	v_fmac_f32_e32 v31, v23, v29
	v_fmac_f32_e32 v32, v23, v30
	v_cvt_pk_bf16_f32 v128, v31, v32
	v_lshlrev_b32_e32 v25, 16, v129
	v_and_b32_e32 v26, 0xffff0000, v129
	v_lshlrev_b32_e32 v27, 16, v133
	v_and_b32_e32 v28, 0xffff0000, v133
	v_lshlrev_b32_e32 v29, 16, v137
	v_and_b32_e32 v30, 0xffff0000, v137
	v_mul_f32_e32 v31, v21, v25
	v_mul_f32_e32 v32, v22, v28
	v_fmac_f32_e32 v31, v22, v27
	v_fmac_f32_e32 v32, v21, v26
	v_fmac_f32_e32 v31, v23, v29
	v_fmac_f32_e32 v32, v23, v30
	v_cvt_pk_bf16_f32 v129, v31, v32
	v_lshlrev_b32_e32 v25, 16, v130
	v_and_b32_e32 v26, 0xffff0000, v130
	v_lshlrev_b32_e32 v27, 16, v134
	v_and_b32_e32 v28, 0xffff0000, v134
	v_lshlrev_b32_e32 v29, 16, v138
	v_and_b32_e32 v30, 0xffff0000, v138
	v_mul_f32_e32 v31, v21, v25
	v_mul_f32_e32 v32, v22, v28
	v_fmac_f32_e32 v31, v22, v27
	v_fmac_f32_e32 v32, v21, v26
	v_fmac_f32_e32 v31, v23, v29
	v_fmac_f32_e32 v32, v23, v30
	v_cvt_pk_bf16_f32 v130, v31, v32
	v_lshlrev_b32_e32 v25, 16, v131
	v_and_b32_e32 v26, 0xffff0000, v131
	v_lshlrev_b32_e32 v27, 16, v135
	v_and_b32_e32 v28, 0xffff0000, v135
	v_lshlrev_b32_e32 v29, 16, v139
	v_and_b32_e32 v30, 0xffff0000, v139
	v_mul_f32_e32 v31, v21, v25
	v_mul_f32_e32 v32, v22, v28
	v_fmac_f32_e32 v31, v22, v27
	v_fmac_f32_e32 v32, v21, v26
	v_fmac_f32_e32 v31, v23, v29
	v_fmac_f32_e32 v32, v23, v30
	v_cvt_pk_bf16_f32 v131, v31, v32
	global_store_dwordx4 v14, v[128:131], s[8:9]
	s_add_u32 s8, s8, 0x200000
	s_addc_u32 s9, s9, 0
	v_max3_f32 v20, v188, v189, v190
	v_sub_f32_e32 v21, v188, v20
	v_sub_f32_e32 v22, v189, v20
	v_sub_f32_e32 v23, v190, v20
	v_mul_f32_e32 v21, 0x3fb8aa3b, v21
	v_mul_f32_e32 v22, 0x3fb8aa3b, v22
	v_mul_f32_e32 v23, 0x3fb8aa3b, v23
	v_exp_f32_e32 v21, v21
	v_exp_f32_e32 v22, v22
	v_exp_f32_e32 v23, v23
	s_nop 0
	v_add_f32_e32 v24, v21, v22
	v_add_f32_e32 v24, v23, v24
	v_rcp_f32_e32 v24, v24
	s_nop 0
	v_mul_f32_e32 v21, v21, v24
	v_mul_f32_e32 v22, v22, v24
	v_mul_f32_e32 v23, v23, v24
	s_waitcnt vmcnt(9)
	v_lshlrev_b32_e32 v25, 16, v140
	v_and_b32_e32 v26, 0xffff0000, v140
	v_lshlrev_b32_e32 v27, 16, v144
	v_and_b32_e32 v28, 0xffff0000, v144
	v_lshlrev_b32_e32 v29, 16, v148
	v_and_b32_e32 v30, 0xffff0000, v148
	v_mul_f32_e32 v31, v21, v25
	v_mul_f32_e32 v32, v22, v28
	v_fmac_f32_e32 v31, v22, v27
	v_fmac_f32_e32 v32, v21, v26
	v_fmac_f32_e32 v31, v23, v29
	v_fmac_f32_e32 v32, v23, v30
	v_cvt_pk_bf16_f32 v140, v31, v32
	v_lshlrev_b32_e32 v25, 16, v141
	v_and_b32_e32 v26, 0xffff0000, v141
	v_lshlrev_b32_e32 v27, 16, v145
	v_and_b32_e32 v28, 0xffff0000, v145
	v_lshlrev_b32_e32 v29, 16, v149
	v_and_b32_e32 v30, 0xffff0000, v149
	v_mul_f32_e32 v31, v21, v25
	v_mul_f32_e32 v32, v22, v28
	v_fmac_f32_e32 v31, v22, v27
	v_fmac_f32_e32 v32, v21, v26
	v_fmac_f32_e32 v31, v23, v29
	v_fmac_f32_e32 v32, v23, v30
	v_cvt_pk_bf16_f32 v141, v31, v32
	v_lshlrev_b32_e32 v25, 16, v142
	v_and_b32_e32 v26, 0xffff0000, v142
	v_lshlrev_b32_e32 v27, 16, v146
	v_and_b32_e32 v28, 0xffff0000, v146
	v_lshlrev_b32_e32 v29, 16, v150
	v_and_b32_e32 v30, 0xffff0000, v150
	v_mul_f32_e32 v31, v21, v25
	v_mul_f32_e32 v32, v22, v28
	v_fmac_f32_e32 v31, v22, v27
	v_fmac_f32_e32 v32, v21, v26
	v_fmac_f32_e32 v31, v23, v29
	v_fmac_f32_e32 v32, v23, v30
	v_cvt_pk_bf16_f32 v142, v31, v32
	v_lshlrev_b32_e32 v25, 16, v143
	v_and_b32_e32 v26, 0xffff0000, v143
	v_lshlrev_b32_e32 v27, 16, v147
	v_and_b32_e32 v28, 0xffff0000, v147
	v_lshlrev_b32_e32 v29, 16, v151
	v_and_b32_e32 v30, 0xffff0000, v151
	v_mul_f32_e32 v31, v21, v25
	v_mul_f32_e32 v32, v22, v28
	v_fmac_f32_e32 v31, v22, v27
	v_fmac_f32_e32 v32, v21, v26
	v_fmac_f32_e32 v31, v23, v29
	v_fmac_f32_e32 v32, v23, v30
	v_cvt_pk_bf16_f32 v143, v31, v32
	global_store_dwordx4 v14, v[140:143], s[8:9]
	s_add_u32 s8, s8, 0x200000
	s_addc_u32 s9, s9, 0
	v_max3_f32 v20, v191, v192, v193
	v_sub_f32_e32 v21, v191, v20
	v_sub_f32_e32 v22, v192, v20
	v_sub_f32_e32 v23, v193, v20
	v_mul_f32_e32 v21, 0x3fb8aa3b, v21
	v_mul_f32_e32 v22, 0x3fb8aa3b, v22
	v_mul_f32_e32 v23, 0x3fb8aa3b, v23
	v_exp_f32_e32 v21, v21
	v_exp_f32_e32 v22, v22
	v_exp_f32_e32 v23, v23
	s_nop 0
	v_add_f32_e32 v24, v21, v22
	v_add_f32_e32 v24, v23, v24
	v_rcp_f32_e32 v24, v24
	s_nop 0
	v_mul_f32_e32 v21, v21, v24
	v_mul_f32_e32 v22, v22, v24
	v_mul_f32_e32 v23, v23, v24
	s_waitcnt vmcnt(7)
	v_lshlrev_b32_e32 v25, 16, v152
	v_and_b32_e32 v26, 0xffff0000, v152
	v_lshlrev_b32_e32 v27, 16, v156
	v_and_b32_e32 v28, 0xffff0000, v156
	v_lshlrev_b32_e32 v29, 16, v160
	v_and_b32_e32 v30, 0xffff0000, v160
	v_mul_f32_e32 v31, v21, v25
	v_mul_f32_e32 v32, v22, v28
	v_fmac_f32_e32 v31, v22, v27
	v_fmac_f32_e32 v32, v21, v26
	v_fmac_f32_e32 v31, v23, v29
	v_fmac_f32_e32 v32, v23, v30
	v_cvt_pk_bf16_f32 v152, v31, v32
	v_lshlrev_b32_e32 v25, 16, v153
	v_and_b32_e32 v26, 0xffff0000, v153
	v_lshlrev_b32_e32 v27, 16, v157
	v_and_b32_e32 v28, 0xffff0000, v157
	v_lshlrev_b32_e32 v29, 16, v161
	v_and_b32_e32 v30, 0xffff0000, v161
	v_mul_f32_e32 v31, v21, v25
	v_mul_f32_e32 v32, v22, v28
	v_fmac_f32_e32 v31, v22, v27
	v_fmac_f32_e32 v32, v21, v26
	v_fmac_f32_e32 v31, v23, v29
	v_fmac_f32_e32 v32, v23, v30
	v_cvt_pk_bf16_f32 v153, v31, v32
	v_lshlrev_b32_e32 v25, 16, v154
	v_and_b32_e32 v26, 0xffff0000, v154
	v_lshlrev_b32_e32 v27, 16, v158
	v_and_b32_e32 v28, 0xffff0000, v158
	v_lshlrev_b32_e32 v29, 16, v162
	v_and_b32_e32 v30, 0xffff0000, v162
	v_mul_f32_e32 v31, v21, v25
	v_mul_f32_e32 v32, v22, v28
	v_fmac_f32_e32 v31, v22, v27
	v_fmac_f32_e32 v32, v21, v26
	v_fmac_f32_e32 v31, v23, v29
	v_fmac_f32_e32 v32, v23, v30
	v_cvt_pk_bf16_f32 v154, v31, v32
	v_lshlrev_b32_e32 v25, 16, v155
	v_and_b32_e32 v26, 0xffff0000, v155
	v_lshlrev_b32_e32 v27, 16, v159
	v_and_b32_e32 v28, 0xffff0000, v159
	v_lshlrev_b32_e32 v29, 16, v163
	v_and_b32_e32 v30, 0xffff0000, v163
	v_mul_f32_e32 v31, v21, v25
	v_mul_f32_e32 v32, v22, v28
	v_fmac_f32_e32 v31, v22, v27
	v_fmac_f32_e32 v32, v21, v26
	v_fmac_f32_e32 v31, v23, v29
	v_fmac_f32_e32 v32, v23, v30
	v_cvt_pk_bf16_f32 v155, v31, v32
	global_store_dwordx4 v14, v[152:155], s[8:9]
	s_mov_b64 s[10:11], exec
	s_mov_b32 s12, 0xfffff
	s_mov_b32 s13, 0
	s_mov_b64 s[0:1], exec
	s_branch .LBB0_754
